# v79 + nt on the read-once A-operand LDS-DMA loads of the E and Y GEMMs (S-chain streaming out of L2)
# baseline (speedup 1.0000x reference)
.LBB0_531:
	s_or_b64 exec, exec, s[4:5]
	s_and_b64 s[4:5], s[48:49], exec
	v_readlane_b32 s8, v255, 4
	s_mov_b64 s[4:5], s[0:1]
	s_mov_b64 s[6:7], s[0:1]
	v_mov_b32_e32 v10, v0
	v_readlane_b32 s9, v255, 5
	s_cselect_b32 s36, 0xa0, s33
	s_waitcnt lgkmcnt(0)
	s_barrier
	s_andn2_b64 vcc, exec, s[8:9]
	v_readfirstlane_b32 s14, v10
	s_cbranch_vccnz .LBB0_547
	v_lshlrev_b32_e32 v1, 4, v10
	v_add_u32_e32 v2, 0x2000, v1
	v_ashrrev_i32_e32 v3, 31, v2
	v_lshrrev_b32_e32 v3, 22, v3
	v_add_u32_e32 v3, v2, v3
	v_ashrrev_i32_e32 v3, 10, v3
	v_mul_i32_i24_e32 v5, 0x400, v3
	v_sub_u32_e32 v2, v2, v5
	v_lshrrev_b32_e32 v5, 4, v2
	v_bitop3_b32 v2, v5, v2, 32 bitop3:0x6c
	v_ashrrev_i32_e32 v5, 31, v2
	v_lshrrev_b32_e32 v5, 26, v5
	v_add_u32_e32 v5, v2, v5
	v_lshrrev_b32_e32 v6, 6, v5
	v_and_b32_e32 v5, 0xc0, v5
	s_load_dwordx2 s[4:5], s[4:5], 0xe0
	v_lshlrev_b32_e32 v4, 5, v3
	v_sub_u32_e32 v2, v2, v5
	v_mov_b32_e32 v5, 1
	v_and_b32_e32 v4, 32, v4
	v_ashrrev_i16_sdwa v2, v5, sext(v2) dst_sel:DWORD dst_unused:UNUSED_PAD src0_sel:DWORD src1_sel:BYTE_0
	v_add_u32_sdwa v2, v4, sext(v2) dst_sel:DWORD dst_unused:UNUSED_PAD src0_sel:DWORD src1_sel:WORD_0
	v_bfe_i32 v4, v10, 27, 1
	v_lshrrev_b32_e32 v4, 22, v4
	v_add_u32_e32 v4, v1, v4
	s_waitcnt lgkmcnt(0)
	s_add_u32 s28, s4, 0xa400000
	v_and_b32_e32 v4, 0xfffffc00, v4
	s_addc_u32 s29, s5, 0
	v_lshlrev_b32_e32 v3, 3, v3
	v_sub_u32_e32 v1, v1, v4
	s_add_u32 s30, s4, 0x1e00000
	v_and_b32_e32 v3, 0x7ffff0, v3
	v_lshrrev_b32_e32 v4, 4, v1
	s_mul_hi_i32 s4, s2, 0x66666667
	s_addc_u32 s31, s5, 0
	v_add_lshl_u32 v3, v6, v3, 9
	v_bitop3_b32 v1, v4, v1, 32 bitop3:0x6c
	s_lshr_b32 s5, s4, 31
	s_ashr_i32 s4, s4, 1
	v_lshl_add_u32 v130, v2, 1, v3
	v_ashrrev_i32_e32 v2, 31, v10
	v_ashrrev_i32_e32 v4, 31, v1
	s_add_i32 s4, s4, s5
	v_lshrrev_b32_e32 v2, 26, v2
	v_lshrrev_b32_e32 v4, 26, v4
	s_mul_i32 s5, s4, 5
	v_add_u32_e32 v2, v10, v2
	v_add_u32_e32 v4, v1, v4
	s_sub_i32 s10, s2, s5
	s_ashr_i32 s8, s14, 6
	v_ashrrev_i32_e32 v2, 6, v2
	v_lshrrev_b32_e32 v6, 6, v4
	v_and_b32_e32 v4, 0xc0, v4
	s_ashr_i32 s5, s4, 31
	s_ashr_i32 s11, s10, 31
	s_ashr_i32 s15, s14, 8
	s_lshl_b32 s18, s8, 10
	v_add_u32_e32 v132, v130, v3
	v_lshlrev_b32_e32 v3, 5, v2
	v_sub_u32_e32 v1, v1, v4
	v_lshlrev_b32_e32 v2, 3, v2
	s_lshl_b64 s[12:13], s[10:11], 18
	s_lshl_b64 s[16:17], s[4:5], 17
	v_and_b32_e32 v3, 32, v3
	v_ashrrev_i16_sdwa v1, v5, sext(v1) dst_sel:DWORD dst_unused:UNUSED_PAD src0_sel:DWORD src1_sel:BYTE_0
	v_and_b32_e32 v2, 0x7ffff0, v2
	s_add_u32 s96, s30, s16
	v_add_u32_sdwa v1, v3, sext(v1) dst_sel:DWORD dst_unused:UNUSED_PAD src0_sel:DWORD src1_sel:WORD_0
	v_add_lshl_u32 v2, v6, v2, 9
	s_addc_u32 s97, s31, s17
	s_add_i32 s11, s18, 0
	v_lshl_add_u32 v134, v1, 1, v2
	s_add_i32 m0, s11, 0x10000
	s_mul_i32 s19, s4, 0x140000
	global_load_lds_dwordx4 v134, s[96:97]
	s_add_i32 m0, s11, 0x12000
	s_add_u32 s16, s96, 0x10000
	global_load_lds_dwordx4 v130, s[96:97]
	s_addc_u32 s17, s97, 0
	s_add_i32 m0, s11, 0x14000
	s_mul_hi_i32 s9, s4, 0x140000
	global_load_lds_dwordx4 v134, s[16:17]
	s_add_i32 m0, s11, 0x16000
	s_add_u32 s5, s28, s12
	s_addc_u32 s12, s29, s13
	s_add_u32 s22, s5, s19
	s_addc_u32 s23, s12, s9
	s_add_i32 s34, s11, 0x2000
	v_add_u32_e32 v136, v134, v2
	global_load_lds_dwordx4 v130, s[16:17]
	s_mov_b32 m0, s11
	s_add_u32 s12, s22, 0x20000
	global_load_lds_dwordx4 v136, s[22:23] nt
	s_mov_b32 m0, s34
	s_addc_u32 s13, s23, 0
	s_add_i32 s35, s11, 0x4000
	global_load_lds_dwordx4 v132, s[22:23] nt
	s_mov_b32 m0, s35
	s_add_i32 s37, s11, 0x6000
	global_load_lds_dwordx4 v136, s[12:13] nt
	s_mov_b32 m0, s37
	v_mov_b32_e32 v135, 0
	global_load_lds_dwordx4 v132, s[12:13] nt
	s_load_dwordx2 s[12:13], s[6:7], 0xd8
	v_mov_b32_e32 v131, v135
	v_mov_b32_e32 v137, v135
	v_mov_b32_e32 v133, v135
	s_cmp_eq_u32 s15, 1
	v_lshl_add_u64 v[8:9], s[96:97], 0, v[134:135]
	v_lshl_add_u64 v[6:7], s[96:97], 0, v[130:131]
	v_lshl_add_u64 v[2:3], s[22:23], 0, v[136:137]
	s_cselect_b64 s[6:7], -1, 0
	s_cmp_lg_u32 s15, 1
	v_lshl_add_u64 v[4:5], s[22:23], 0, v[132:133]
	s_cbranch_scc1 .LBB0_534
	s_barrier
.LBB0_534:
	s_lshl_b32 s8, s8, 5
	s_and_b32 s19, s8, 0x60
	s_mov_b64 s[8:9], 0x80
	s_add_i32 m0, s11, 0x18000
	v_lshl_add_u64 v[8:9], v[8:9], 0, s[8:9]
	s_lshl_b32 s5, s15, 13
	s_lshl_b32 s20, s19, 7
	s_waitcnt vmcnt(2)
	s_barrier
	global_load_lds_dwordx4 v[8:9], off
	v_lshl_add_u64 v[6:7], v[6:7], 0, s[8:9]
	s_add_i32 m0, s11, 0x1a000
	s_add_i32 s44, s11, 0x8000
	s_add_i32 s45, s11, 0xa000
	global_load_lds_dwordx4 v[6:7], off
	v_lshl_add_u64 v[2:3], v[2:3], 0, s[8:9]
	s_mov_b32 m0, s44
	s_add_u32 s16, s96, 0x10080
	global_load_lds_dwordx4 v[2:3], off nt
	v_lshl_add_u64 v[2:3], v[4:5], 0, s[8:9]
	s_mov_b32 m0, s45
	s_addc_u32 s17, s97, 0
	global_load_lds_dwordx4 v[2:3], off nt
	s_add_i32 m0, s11, 0x1c000
	v_lshl_add_u64 v[2:3], s[16:17], 0, v[134:135]
	global_load_lds_dwordx4 v[2:3], off
	v_lshl_add_u64 v[2:3], s[16:17], 0, v[130:131]
	s_add_i32 m0, s11, 0x1e000
	v_lshlrev_b32_e32 v4, 2, v10
	global_load_lds_dwordx4 v[2:3], off
	v_and_b32_e32 v3, 15, v10
	v_and_b32_e32 v2, 48, v10
	v_lshl_or_b32 v1, s15, 6, v3
	v_lshl_or_b32 v3, v3, 6, v2
	v_and_b32_e32 v4, 32, v4
	s_cmpk_lt_u32 s14, 0x100
	v_bitop3_b32 v5, v3, s5, v4 bitop3:0xde
	v_bitop3_b32 v4, v3, s20, v4 bitop3:0xde
	s_cselect_b64 s[20:21], -1, 0
	s_ashr_i32 s46, s36, 31
	s_ashr_i32 s5, s2, 31
	s_lshl_b32 s14, s19, 2
	s_waitcnt lgkmcnt(0)
	s_add_u32 s12, s12, s14
	s_addc_u32 s13, s13, 0
	v_mov_b32_e32 v3, v135
	v_lshl_add_u64 v[138:139], s[12:13], 0, v[2:3]
	s_add_u32 s12, s36, s2
	s_waitcnt vmcnt(6)
	s_addc_u32 s13, s46, s5
	s_add_i32 s56, 0, 0x14000
	s_add_i32 s90, 0, 0x18000
	s_add_i32 s92, 0, 0x1c000
	v_add_u32_e32 v145, s56, v4
	v_cndmask_b32_e64 v2, 0, 1, s[20:21]
	s_add_i32 s54, s3, s18
	s_add_i32 s56, s56, s18
	v_add_u32_e32 v147, s90, v4
	v_add_u32_e32 v148, s92, v4
	s_add_i32 s90, s90, s18
	s_add_i32 s92, s92, s18
	v_add_u32_e32 v144, s3, v4
	v_add_u32_e32 v146, 0, v5
	s_mov_b64 s[14:15], 0x100
	s_mov_b64 s[16:17], 0x180
	s_add_i32 s52, s11, 0xc000
	s_add_i32 s53, s11, 0xe000
	s_add_i32 s55, s54, 0x2000
	s_add_i32 s57, s56, 0x2000
	s_add_i32 s91, s90, 0x2000
	s_add_i32 s93, s92, 0x2000
	v_cmp_ne_u32_e64 s[38:39], 1, v2
	v_mov_b32_e32 v149, 0x500
	s_barrier
	s_branch .LBB0_537

.LBB0_541:
	ds_read_b128 v[2:5], v144
	ds_read_b128 v[6:9], v144 offset:1024
	ds_read_b128 v[10:13], v144 offset:2048
	ds_read_b128 v[14:17], v144 offset:3072
	ds_read_b128 v[18:21], v145
	ds_read_b128 v[22:25], v145 offset:1024
	ds_read_b128 v[26:29], v145 offset:2048
	ds_read_b128 v[30:33], v145 offset:3072
	s_lshl_b64 s[26:27], s[18:19], 17
	s_add_u32 s26, s30, s26
	s_addc_u32 s27, s31, s27
	s_and_b64 s[42:43], s[42:43], exec
	s_cselect_b32 s43, s27, s97
	s_cselect_b32 s42, s26, s96
	s_add_u32 vcc_lo, s22, 0x20080
	s_addc_u32 vcc_hi, s23, 0
	s_mov_b32 m0, s52
	v_lshl_add_u64 v[66:67], vcc, 0, v[136:137]
	ds_read_b128 v[34:37], v146
	ds_read_b128 v[38:41], v146 offset:1024
	ds_read_b128 v[42:45], v146 offset:2048
	ds_read_b128 v[46:49], v146 offset:3072
	ds_read_b128 v[50:53], v146 offset:4096
	ds_read_b128 v[54:57], v146 offset:5120
	ds_read_b128 v[58:61], v146 offset:6144
	ds_read_b128 v[62:65], v146 offset:7168
	global_load_lds_dwordx4 v[66:67], off nt
	v_lshl_add_u64 v[66:67], vcc, 0, v[132:133]
	s_mov_b32 m0, s53
	s_nop 0
	global_load_lds_dwordx4 v[66:67], off nt
	s_waitcnt vmcnt(8)
	s_waitcnt lgkmcnt(0)
	s_barrier
	s_setprio 1
	s_waitcnt lgkmcnt(0)
	v_mfma_f32_16x16x32_bf16 v[66:69], v[2:5], v[34:37], 0
	v_mfma_f32_16x16x32_bf16 v[70:73], v[10:13], v[34:37], 0
	v_mfma_f32_16x16x32_bf16 v[74:77], v[2:5], v[42:45], 0
	v_mfma_f32_16x16x32_bf16 v[78:81], v[10:13], v[42:45], 0
	v_mfma_f32_16x16x32_bf16 v[82:85], v[2:5], v[50:53], 0
	v_mfma_f32_16x16x32_bf16 v[86:89], v[10:13], v[50:53], 0
	v_mfma_f32_16x16x32_bf16 v[90:93], v[2:5], v[58:61], 0
	v_mfma_f32_16x16x32_bf16 v[94:97], v[10:13], v[58:61], 0
	v_mfma_f32_16x16x32_bf16 v[66:69], v[6:9], v[38:41], v[66:69]
	v_mfma_f32_16x16x32_bf16 v[70:73], v[14:17], v[38:41], v[70:73]
	v_mfma_f32_16x16x32_bf16 v[74:77], v[6:9], v[46:49], v[74:77]
	v_mfma_f32_16x16x32_bf16 v[78:81], v[14:17], v[46:49], v[78:81]
	v_mfma_f32_16x16x32_bf16 v[82:85], v[6:9], v[54:57], v[82:85]
	v_mfma_f32_16x16x32_bf16 v[86:89], v[14:17], v[54:57], v[86:89]
	v_mfma_f32_16x16x32_bf16 v[90:93], v[6:9], v[62:65], v[90:93]
	v_mfma_f32_16x16x32_bf16 v[94:97], v[14:17], v[62:65], v[94:97]
	s_setprio 0
	s_setprio 1
	v_mfma_f32_16x16x32_bf16 v[98:101], v[18:21], v[34:37], 0
	v_mfma_f32_16x16x32_bf16 v[34:37], v[26:29], v[34:37], 0
	v_mfma_f32_16x16x32_bf16 v[98:101], v[22:25], v[38:41], v[98:101]
	v_mfma_f32_16x16x32_bf16 v[34:37], v[30:33], v[38:41], v[34:37]
	v_mfma_f32_16x16x32_bf16 v[38:41], v[18:21], v[42:45], 0
	v_mfma_f32_16x16x32_bf16 v[42:45], v[26:29], v[42:45], 0
	v_mfma_f32_16x16x32_bf16 v[38:41], v[22:25], v[46:49], v[38:41]
	v_mfma_f32_16x16x32_bf16 v[42:45], v[30:33], v[46:49], v[42:45]
	v_mfma_f32_16x16x32_bf16 v[46:49], v[18:21], v[50:53], 0
	v_mfma_f32_16x16x32_bf16 v[50:53], v[26:29], v[50:53], 0
	v_mfma_f32_16x16x32_bf16 v[46:49], v[22:25], v[54:57], v[46:49]
	v_mfma_f32_16x16x32_bf16 v[50:53], v[30:33], v[54:57], v[50:53]
	v_mfma_f32_16x16x32_bf16 v[54:57], v[18:21], v[58:61], 0
	v_mfma_f32_16x16x32_bf16 v[58:61], v[26:29], v[58:61], 0
	v_mfma_f32_16x16x32_bf16 v[54:57], v[22:25], v[62:65], v[54:57]
	v_mfma_f32_16x16x32_bf16 v[58:61], v[30:33], v[62:65], v[58:61]
	s_setprio 0
	s_barrier
	v_lshl_add_u64 v[214:215], s[96:97], 0, v[134:135]
	s_mov_b32 m0, s54
	v_lshl_add_u64 v[150:151], v[214:215], 0, s[14:15]
	v_lshl_add_u64 v[216:217], s[96:97], 0, v[130:131]
	s_add_u32 vcc_lo, s96, 0x10100
	ds_read_b128 v[62:65], v146 offset:16384
	ds_read_b128 v[102:105], v146 offset:17408
	ds_read_b128 v[106:109], v146 offset:18432
	ds_read_b128 v[110:113], v146 offset:19456
	ds_read_b128 v[114:117], v146 offset:20480
	ds_read_b128 v[118:121], v146 offset:21504
	ds_read_b128 v[122:125], v146 offset:22528
	ds_read_b128 v[126:129], v146 offset:23552
	global_load_lds_dwordx4 v[150:151], off
	v_lshl_add_u64 v[150:151], v[216:217], 0, s[14:15]
	s_mov_b32 m0, s55
	s_addc_u32 vcc_hi, s97, 0
	global_load_lds_dwordx4 v[150:151], off
	v_lshl_add_u64 v[150:151], vcc, 0, v[134:135]
	s_mov_b32 m0, s56
	v_lshl_add_u64 v[218:219], s[22:23], 0, v[136:137]
	global_load_lds_dwordx4 v[150:151], off
	v_lshl_add_u64 v[150:151], vcc, 0, v[130:131]
	s_mov_b32 m0, s57
	v_lshl_add_u64 v[220:221], s[22:23], 0, v[132:133]
	global_load_lds_dwordx4 v[150:151], off
	v_lshl_add_u64 v[150:151], v[218:219], 0, s[14:15]
	s_mov_b32 m0, s11
	s_nop 0
	global_load_lds_dwordx4 v[150:151], off nt
	v_lshl_add_u64 v[150:151], v[220:221], 0, s[14:15]
	s_mov_b32 m0, s34
	s_nop 0
	global_load_lds_dwordx4 v[150:151], off nt
	s_waitcnt vmcnt(8)
	s_waitcnt lgkmcnt(0)
	s_barrier
	s_setprio 1
	s_waitcnt lgkmcnt(0)
	v_mfma_f32_16x16x32_bf16 v[150:153], v[2:5], v[62:65], 0
	v_mfma_f32_16x16x32_bf16 v[158:161], v[2:5], v[106:109], 0
	v_mfma_f32_16x16x32_bf16 v[166:169], v[2:5], v[114:117], 0
	v_mfma_f32_16x16x32_bf16 v[2:5], v[2:5], v[122:125], 0
	v_mfma_f32_16x16x32_bf16 v[150:153], v[6:9], v[102:105], v[150:153]
	v_mfma_f32_16x16x32_bf16 v[158:161], v[6:9], v[110:113], v[158:161]
	v_mfma_f32_16x16x32_bf16 v[166:169], v[6:9], v[118:121], v[166:169]
	v_mfma_f32_16x16x32_bf16 v[2:5], v[6:9], v[126:129], v[2:5]
	v_mfma_f32_16x16x32_bf16 v[6:9], v[10:13], v[122:125], 0
	v_mfma_f32_16x16x32_bf16 v[154:157], v[10:13], v[62:65], 0
	v_mfma_f32_16x16x32_bf16 v[162:165], v[10:13], v[106:109], 0
	v_mfma_f32_16x16x32_bf16 v[170:173], v[10:13], v[114:117], 0
	v_mfma_f32_16x16x32_bf16 v[6:9], v[14:17], v[126:129], v[6:9]
	v_mfma_f32_16x16x32_bf16 v[154:157], v[14:17], v[102:105], v[154:157]
	v_mfma_f32_16x16x32_bf16 v[162:165], v[14:17], v[110:113], v[162:165]
	v_mfma_f32_16x16x32_bf16 v[170:173], v[14:17], v[118:121], v[170:173]
	s_setprio 0
	s_setprio 1
	v_mfma_f32_16x16x32_bf16 v[10:13], v[18:21], v[62:65], 0
	v_mfma_f32_16x16x32_bf16 v[14:17], v[26:29], v[62:65], 0
	v_mfma_f32_16x16x32_bf16 v[10:13], v[22:25], v[102:105], v[10:13]
	v_mfma_f32_16x16x32_bf16 v[14:17], v[30:33], v[102:105], v[14:17]
	v_mfma_f32_16x16x32_bf16 v[62:65], v[18:21], v[106:109], 0
	v_mfma_f32_16x16x32_bf16 v[102:105], v[26:29], v[106:109], 0
	v_mfma_f32_16x16x32_bf16 v[106:109], v[18:21], v[114:117], 0
	v_mfma_f32_16x16x32_bf16 v[18:21], v[18:21], v[122:125], 0
	v_mfma_f32_16x16x32_bf16 v[62:65], v[22:25], v[110:113], v[62:65]
	v_mfma_f32_16x16x32_bf16 v[102:105], v[30:33], v[110:113], v[102:105]
	v_mfma_f32_16x16x32_bf16 v[106:109], v[22:25], v[118:121], v[106:109]
	v_mfma_f32_16x16x32_bf16 v[110:113], v[26:29], v[114:117], 0
	v_mfma_f32_16x16x32_bf16 v[18:21], v[22:25], v[126:129], v[18:21]
	v_mfma_f32_16x16x32_bf16 v[22:25], v[26:29], v[122:125], 0
	v_mfma_f32_16x16x32_bf16 v[110:113], v[30:33], v[118:121], v[110:113]
	v_mfma_f32_16x16x32_bf16 v[22:25], v[30:33], v[126:129], v[22:25]
	s_setprio 0
	s_barrier
	ds_read_b128 v[26:29], v147
	ds_read_b128 v[30:33], v147 offset:1024
	ds_read_b128 v[114:117], v147 offset:2048
	ds_read_b128 v[118:121], v147 offset:3072
	ds_read_b128 v[122:125], v148
	ds_read_b128 v[126:129], v148 offset:1024
	ds_read_b128 v[174:177], v148 offset:2048
	ds_read_b128 v[178:181], v148 offset:3072
	s_add_u32 vcc_lo, s22, 0x20100
	s_addc_u32 vcc_hi, s23, 0
	s_mov_b32 m0, s35
	v_lshl_add_u64 v[222:223], vcc, 0, v[136:137]
	ds_read_b128 v[182:185], v146 offset:32768
	ds_read_b128 v[186:189], v146 offset:33792
	ds_read_b128 v[190:193], v146 offset:34816
	ds_read_b128 v[194:197], v146 offset:35840
	ds_read_b128 v[198:201], v146 offset:36864
	ds_read_b128 v[202:205], v146 offset:37888
	ds_read_b128 v[206:209], v146 offset:38912
	ds_read_b128 v[210:213], v146 offset:39936
	global_load_lds_dwordx4 v[222:223], off nt
	v_lshl_add_u64 v[222:223], vcc, 0, v[132:133]
	s_mov_b32 m0, s37
	s_nop 0
	global_load_lds_dwordx4 v[222:223], off nt
	s_waitcnt vmcnt(8)
	s_waitcnt lgkmcnt(0)
	s_barrier
	s_setprio 1
	s_waitcnt lgkmcnt(0)
	v_mfma_f32_16x16x32_bf16 v[66:69], v[26:29], v[182:185], v[66:69]
	v_mfma_f32_16x16x32_bf16 v[70:73], v[114:117], v[182:185], v[70:73]
	v_mfma_f32_16x16x32_bf16 v[74:77], v[26:29], v[190:193], v[74:77]
	v_mfma_f32_16x16x32_bf16 v[78:81], v[114:117], v[190:193], v[78:81]
	v_mfma_f32_16x16x32_bf16 v[82:85], v[26:29], v[198:201], v[82:85]
	v_mfma_f32_16x16x32_bf16 v[86:89], v[114:117], v[198:201], v[86:89]
	v_mfma_f32_16x16x32_bf16 v[90:93], v[26:29], v[206:209], v[90:93]
	v_mfma_f32_16x16x32_bf16 v[94:97], v[114:117], v[206:209], v[94:97]
	v_mfma_f32_16x16x32_bf16 v[66:69], v[30:33], v[186:189], v[66:69]
	v_mfma_f32_16x16x32_bf16 v[70:73], v[118:121], v[186:189], v[70:73]
	v_mfma_f32_16x16x32_bf16 v[74:77], v[30:33], v[194:197], v[74:77]
	v_mfma_f32_16x16x32_bf16 v[78:81], v[118:121], v[194:197], v[78:81]
	v_mfma_f32_16x16x32_bf16 v[82:85], v[30:33], v[202:205], v[82:85]
	v_mfma_f32_16x16x32_bf16 v[86:89], v[118:121], v[202:205], v[86:89]
	v_mfma_f32_16x16x32_bf16 v[90:93], v[30:33], v[210:213], v[90:93]
	v_mfma_f32_16x16x32_bf16 v[94:97], v[118:121], v[210:213], v[94:97]
	s_setprio 0
	s_setprio 1
	v_mfma_f32_16x16x32_bf16 v[98:101], v[122:125], v[182:185], v[98:101]
	v_mfma_f32_16x16x32_bf16 v[34:37], v[174:177], v[182:185], v[34:37]
	v_mfma_f32_16x16x32_bf16 v[38:41], v[122:125], v[190:193], v[38:41]
	v_mfma_f32_16x16x32_bf16 v[42:45], v[174:177], v[190:193], v[42:45]
	v_mfma_f32_16x16x32_bf16 v[46:49], v[122:125], v[198:201], v[46:49]
	v_mfma_f32_16x16x32_bf16 v[50:53], v[174:177], v[198:201], v[50:53]
	v_mfma_f32_16x16x32_bf16 v[54:57], v[122:125], v[206:209], v[54:57]
	v_mfma_f32_16x16x32_bf16 v[58:61], v[174:177], v[206:209], v[58:61]
	v_mfma_f32_16x16x32_bf16 v[98:101], v[126:129], v[186:189], v[98:101]
	v_mfma_f32_16x16x32_bf16 v[34:37], v[178:181], v[186:189], v[34:37]
	v_mfma_f32_16x16x32_bf16 v[38:41], v[126:129], v[194:197], v[38:41]
	v_mfma_f32_16x16x32_bf16 v[42:45], v[178:181], v[194:197], v[42:45]
	v_mfma_f32_16x16x32_bf16 v[46:49], v[126:129], v[202:205], v[46:49]
	v_mfma_f32_16x16x32_bf16 v[50:53], v[178:181], v[202:205], v[50:53]
	v_mfma_f32_16x16x32_bf16 v[54:57], v[126:129], v[210:213], v[54:57]
	v_mfma_f32_16x16x32_bf16 v[58:61], v[178:181], v[210:213], v[58:61]
	s_setprio 0
	s_barrier
	s_mov_b32 m0, s90
	v_lshl_add_u64 v[214:215], v[214:215], 0, s[16:17]
	s_add_u32 s96, s96, 0x10180
	ds_read_b128 v[182:185], v146 offset:49152
	ds_read_b128 v[186:189], v146 offset:50176
	ds_read_b128 v[190:193], v146 offset:51200
	ds_read_b128 v[194:197], v146 offset:52224
	ds_read_b128 v[198:201], v146 offset:53248
	ds_read_b128 v[202:205], v146 offset:54272
	ds_read_b128 v[206:209], v146 offset:55296
	ds_read_b128 v[210:213], v146 offset:56320
	global_load_lds_dwordx4 v[214:215], off
	v_lshl_add_u64 v[214:215], v[216:217], 0, s[16:17]
	s_mov_b32 m0, s91
	s_addc_u32 s97, s97, 0
	global_load_lds_dwordx4 v[214:215], off
	v_lshl_add_u64 v[214:215], s[96:97], 0, v[134:135]
	s_mov_b32 m0, s92
	s_nop 0
	global_load_lds_dwordx4 v[214:215], off
	v_lshl_add_u64 v[214:215], s[96:97], 0, v[130:131]
	s_mov_b32 m0, s93
	s_nop 0
	global_load_lds_dwordx4 v[214:215], off
	v_lshl_add_u64 v[214:215], v[218:219], 0, s[16:17]
	s_mov_b32 m0, s44
	s_nop 0
	global_load_lds_dwordx4 v[214:215], off nt
	v_lshl_add_u64 v[214:215], v[220:221], 0, s[16:17]
	s_mov_b32 m0, s45
	s_nop 0
	global_load_lds_dwordx4 v[214:215], off nt
	s_waitcnt vmcnt(8)
	s_waitcnt lgkmcnt(0)
	s_barrier
	s_setprio 1
	s_waitcnt lgkmcnt(0)
	v_mfma_f32_16x16x32_bf16 v[2:5], v[26:29], v[206:209], v[2:5]
	v_mfma_f32_16x16x32_bf16 v[6:9], v[114:117], v[206:209], v[6:9]
	v_mfma_f32_16x16x32_bf16 v[150:153], v[26:29], v[182:185], v[150:153]
	v_mfma_f32_16x16x32_bf16 v[154:157], v[114:117], v[182:185], v[154:157]
	v_mfma_f32_16x16x32_bf16 v[158:161], v[26:29], v[190:193], v[158:161]
	v_mfma_f32_16x16x32_bf16 v[162:165], v[114:117], v[190:193], v[162:165]
	v_mfma_f32_16x16x32_bf16 v[166:169], v[26:29], v[198:201], v[166:169]
	v_mfma_f32_16x16x32_bf16 v[170:173], v[114:117], v[198:201], v[170:173]
	v_mfma_f32_16x16x32_bf16 v[2:5], v[30:33], v[210:213], v[2:5]
	v_mfma_f32_16x16x32_bf16 v[6:9], v[118:121], v[210:213], v[6:9]
	v_mfma_f32_16x16x32_bf16 v[150:153], v[30:33], v[186:189], v[150:153]
	v_mfma_f32_16x16x32_bf16 v[154:157], v[118:121], v[186:189], v[154:157]
	v_mfma_f32_16x16x32_bf16 v[158:161], v[30:33], v[194:197], v[158:161]
	v_mfma_f32_16x16x32_bf16 v[162:165], v[118:121], v[194:197], v[162:165]
	v_mfma_f32_16x16x32_bf16 v[166:169], v[30:33], v[202:205], v[166:169]
	v_mfma_f32_16x16x32_bf16 v[170:173], v[118:121], v[202:205], v[170:173]
	s_setprio 0
	s_setprio 1
	v_mfma_f32_16x16x32_bf16 v[10:13], v[122:125], v[182:185], v[10:13]
	v_mfma_f32_16x16x32_bf16 v[14:17], v[174:177], v[182:185], v[14:17]
	v_mfma_f32_16x16x32_bf16 v[26:29], v[122:125], v[190:193], v[62:65]
	v_mfma_f32_16x16x32_bf16 v[30:33], v[174:177], v[190:193], v[102:105]
	v_mfma_f32_16x16x32_bf16 v[62:65], v[122:125], v[198:201], v[106:109]
	v_mfma_f32_16x16x32_bf16 v[102:105], v[174:177], v[198:201], v[110:113]
	v_mfma_f32_16x16x32_bf16 v[18:21], v[122:125], v[206:209], v[18:21]
	v_mfma_f32_16x16x32_bf16 v[22:25], v[174:177], v[206:209], v[22:25]
	v_mfma_f32_16x16x32_bf16 v[10:13], v[126:129], v[186:189], v[10:13]
	v_mfma_f32_16x16x32_bf16 v[14:17], v[178:181], v[186:189], v[14:17]
	v_mfma_f32_16x16x32_bf16 v[26:29], v[126:129], v[194:197], v[26:29]
	v_mfma_f32_16x16x32_bf16 v[30:33], v[178:181], v[194:197], v[30:33]
	v_mfma_f32_16x16x32_bf16 v[62:65], v[126:129], v[202:205], v[62:65]
	v_mfma_f32_16x16x32_bf16 v[102:105], v[178:181], v[202:205], v[102:105]
	v_mfma_f32_16x16x32_bf16 v[18:21], v[126:129], v[210:213], v[18:21]
	v_mfma_f32_16x16x32_bf16 v[22:25], v[178:181], v[210:213], v[22:25]
	s_setprio 0
	s_barrier
	ds_read_b128 v[106:109], v144
	ds_read_b128 v[110:113], v144 offset:1024
	ds_read_b128 v[114:117], v144 offset:2048
	ds_read_b128 v[118:121], v144 offset:3072
	ds_read_b128 v[122:125], v145
	ds_read_b128 v[126:129], v145 offset:1024
	ds_read_b128 v[174:177], v145 offset:2048
	ds_read_b128 v[178:181], v145 offset:3072
	s_add_u32 s22, s22, 0x20180
	s_addc_u32 s23, s23, 0
	s_mov_b32 m0, s52
	v_lshl_add_u64 v[214:215], s[22:23], 0, v[136:137]
	ds_read_b128 v[182:185], v146
	ds_read_b128 v[186:189], v146 offset:1024
	ds_read_b128 v[190:193], v146 offset:2048
	ds_read_b128 v[194:197], v146 offset:3072
	ds_read_b128 v[198:201], v146 offset:4096
	ds_read_b128 v[202:205], v146 offset:5120
	ds_read_b128 v[206:209], v146 offset:6144
	ds_read_b128 v[210:213], v146 offset:7168
	global_load_lds_dwordx4 v[214:215], off nt
	v_lshl_add_u64 v[214:215], s[22:23], 0, v[132:133]
	s_mov_b32 m0, s53
	s_nop 0
	global_load_lds_dwordx4 v[214:215], off nt
	s_waitcnt vmcnt(8)
	s_waitcnt lgkmcnt(0)
	s_barrier
	s_setprio 1
	s_waitcnt lgkmcnt(0)
	v_mfma_f32_16x16x32_bf16 v[66:69], v[106:109], v[182:185], v[66:69]
	v_mfma_f32_16x16x32_bf16 v[70:73], v[114:117], v[182:185], v[70:73]
	v_mfma_f32_16x16x32_bf16 v[74:77], v[106:109], v[190:193], v[74:77]
	v_mfma_f32_16x16x32_bf16 v[78:81], v[114:117], v[190:193], v[78:81]
	v_mfma_f32_16x16x32_bf16 v[82:85], v[106:109], v[198:201], v[82:85]
	v_mfma_f32_16x16x32_bf16 v[86:89], v[114:117], v[198:201], v[86:89]
	v_mfma_f32_16x16x32_bf16 v[90:93], v[106:109], v[206:209], v[90:93]
	v_mfma_f32_16x16x32_bf16 v[94:97], v[114:117], v[206:209], v[94:97]
	v_mfma_f32_16x16x32_bf16 v[66:69], v[110:113], v[186:189], v[66:69]
	v_mfma_f32_16x16x32_bf16 v[70:73], v[118:121], v[186:189], v[70:73]
	v_mfma_f32_16x16x32_bf16 v[74:77], v[110:113], v[194:197], v[74:77]
	v_mfma_f32_16x16x32_bf16 v[78:81], v[118:121], v[194:197], v[78:81]
	v_mfma_f32_16x16x32_bf16 v[82:85], v[110:113], v[202:205], v[82:85]
	v_mfma_f32_16x16x32_bf16 v[86:89], v[118:121], v[202:205], v[86:89]
	v_mfma_f32_16x16x32_bf16 v[90:93], v[110:113], v[210:213], v[90:93]
	v_mfma_f32_16x16x32_bf16 v[94:97], v[118:121], v[210:213], v[94:97]
	s_setprio 0
	s_setprio 1
	v_mfma_f32_16x16x32_bf16 v[34:37], v[174:177], v[182:185], v[34:37]
	v_mfma_f32_16x16x32_bf16 v[98:101], v[122:125], v[182:185], v[98:101]
	v_mfma_f32_16x16x32_bf16 v[182:185], v[178:181], v[186:189], v[34:37]
	v_mfma_f32_16x16x32_bf16 v[34:37], v[122:125], v[190:193], v[38:41]
	v_mfma_f32_16x16x32_bf16 v[98:101], v[126:129], v[186:189], v[98:101]
	v_mfma_f32_16x16x32_bf16 v[186:189], v[126:129], v[194:197], v[34:37]
	v_mfma_f32_16x16x32_bf16 v[34:37], v[174:177], v[190:193], v[42:45]
	v_mfma_f32_16x16x32_bf16 v[42:45], v[178:181], v[194:197], v[34:37]
	v_mfma_f32_16x16x32_bf16 v[34:37], v[122:125], v[198:201], v[46:49]
	v_mfma_f32_16x16x32_bf16 v[46:49], v[126:129], v[202:205], v[34:37]
	v_mfma_f32_16x16x32_bf16 v[34:37], v[174:177], v[198:201], v[50:53]
	v_mfma_f32_16x16x32_bf16 v[50:53], v[178:181], v[202:205], v[34:37]
	v_mfma_f32_16x16x32_bf16 v[34:37], v[122:125], v[206:209], v[54:57]
	v_mfma_f32_16x16x32_bf16 v[54:57], v[126:129], v[210:213], v[34:37]
	v_mfma_f32_16x16x32_bf16 v[34:37], v[174:177], v[206:209], v[58:61]
	v_mfma_f32_16x16x32_bf16 v[190:193], v[178:181], v[210:213], v[34:37]
	s_setprio 0
	s_barrier
	s_mov_b32 m0, s54
	v_lshl_add_u64 v[250:251], s[42:43], 0, v[134:135]
	s_add_u32 s22, s42, 0x10000
	s_nop 1
	ds_read_b128 v[34:37], v146 offset:16384
	ds_read_b128 v[38:41], v146 offset:17408
	ds_read_b128 v[58:61], v146 offset:18432
	ds_read_b128 v[194:197], v146 offset:19456
	ds_read_b128 v[198:201], v146 offset:20480
	ds_read_b128 v[202:205], v146 offset:21504
	ds_read_b128 v[206:209], v146 offset:22528
	ds_read_b128 v[210:213], v146 offset:23552
	global_load_lds_dwordx4 v[250:251], off
	v_lshl_add_u64 v[252:253], s[42:43], 0, v[130:131]
	s_mov_b32 m0, s55
	s_addc_u32 s23, s43, 0
	global_load_lds_dwordx4 v[252:253], off
	v_lshl_add_u64 v[214:215], s[22:23], 0, v[134:135]
	s_mov_b32 m0, s56
	v_lshl_add_u64 v[140:141], s[24:25], 0, v[136:137]
	global_load_lds_dwordx4 v[214:215], off
	v_lshl_add_u64 v[214:215], s[22:23], 0, v[130:131]
	s_mov_b32 m0, s57
	v_lshl_add_u64 v[142:143], s[24:25], 0, v[132:133]
	global_load_lds_dwordx4 v[214:215], off
	s_mov_b32 m0, s11
	s_nop 0
	global_load_lds_dwordx4 v[140:141], off nt
	s_mov_b32 m0, s34
	s_nop 0
	global_load_lds_dwordx4 v[142:143], off nt
	s_waitcnt vmcnt(8)
	s_waitcnt lgkmcnt(0)
	s_barrier
	s_setprio 1
	s_waitcnt lgkmcnt(0)
	v_mfma_f32_16x16x32_bf16 v[2:5], v[106:109], v[206:209], v[2:5]
	v_mfma_f32_16x16x32_bf16 v[150:153], v[106:109], v[34:37], v[150:153]
	v_mfma_f32_16x16x32_bf16 v[158:161], v[106:109], v[58:61], v[158:161]
	v_mfma_f32_16x16x32_bf16 v[166:169], v[106:109], v[198:201], v[166:169]
	v_mfma_f32_16x16x32_bf16 v[106:109], v[110:113], v[210:213], v[2:5]
	v_mfma_f32_16x16x32_bf16 v[2:5], v[114:117], v[206:209], v[6:9]
	v_mfma_f32_16x16x32_bf16 v[150:153], v[110:113], v[38:41], v[150:153]
	v_mfma_f32_16x16x32_bf16 v[154:157], v[114:117], v[34:37], v[154:157]
	v_mfma_f32_16x16x32_bf16 v[158:161], v[110:113], v[194:197], v[158:161]
	v_mfma_f32_16x16x32_bf16 v[162:165], v[114:117], v[58:61], v[162:165]
	v_mfma_f32_16x16x32_bf16 v[166:169], v[110:113], v[202:205], v[166:169]
	v_mfma_f32_16x16x32_bf16 v[170:173], v[114:117], v[198:201], v[170:173]
	v_mfma_f32_16x16x32_bf16 v[110:113], v[118:121], v[210:213], v[2:5]
	v_mfma_f32_16x16x32_bf16 v[154:157], v[118:121], v[38:41], v[154:157]
	v_mfma_f32_16x16x32_bf16 v[162:165], v[118:121], v[194:197], v[162:165]
	v_mfma_f32_16x16x32_bf16 v[170:173], v[118:121], v[202:205], v[170:173]
	s_setprio 0
	s_setprio 1
	v_mfma_f32_16x16x32_bf16 v[2:5], v[122:125], v[34:37], v[10:13]
	v_mfma_f32_16x16x32_bf16 v[114:117], v[126:129], v[38:41], v[2:5]
	v_mfma_f32_16x16x32_bf16 v[2:5], v[174:177], v[34:37], v[14:17]
	v_mfma_f32_16x16x32_bf16 v[118:121], v[178:181], v[38:41], v[2:5]
	v_mfma_f32_16x16x32_bf16 v[2:5], v[122:125], v[58:61], v[26:29]
	v_mfma_f32_16x16x32_bf16 v[214:217], v[126:129], v[194:197], v[2:5]
	v_mfma_f32_16x16x32_bf16 v[2:5], v[174:177], v[58:61], v[30:33]
	v_mfma_f32_16x16x32_bf16 v[194:197], v[178:181], v[194:197], v[2:5]
	v_mfma_f32_16x16x32_bf16 v[2:5], v[122:125], v[198:201], v[62:65]
	v_mfma_f32_16x16x32_bf16 v[218:221], v[126:129], v[202:205], v[2:5]
	v_mfma_f32_16x16x32_bf16 v[2:5], v[174:177], v[198:201], v[102:105]
	v_mfma_f32_16x16x32_bf16 v[198:201], v[178:181], v[202:205], v[2:5]
	v_mfma_f32_16x16x32_bf16 v[2:5], v[122:125], v[206:209], v[18:21]
	v_mfma_f32_16x16x32_bf16 v[202:205], v[126:129], v[210:213], v[2:5]
	v_mfma_f32_16x16x32_bf16 v[2:5], v[174:177], v[206:209], v[22:25]
	v_mfma_f32_16x16x32_bf16 v[174:177], v[178:181], v[210:213], v[2:5]
	s_setprio 0
	s_barrier
	ds_read_b128 v[122:125], v147
	ds_read_b128 v[126:129], v147 offset:1024
	ds_read_b128 v[178:181], v147 offset:2048
	ds_read_b128 v[206:209], v147 offset:3072
	ds_read_b128 v[210:213], v148
	ds_read_b128 v[222:225], v148 offset:1024
	ds_read_b128 v[226:229], v148 offset:2048
	ds_read_b128 v[230:233], v148 offset:3072
	s_add_u32 s22, s24, 0x20000
	s_addc_u32 s23, s25, 0
	s_mov_b32 m0, s35
	v_lshl_add_u64 v[2:3], s[22:23], 0, v[136:137]
	ds_read_b128 v[26:29], v146 offset:32768
	ds_read_b128 v[30:33], v146 offset:33792
	ds_read_b128 v[62:65], v146 offset:34816
	ds_read_b128 v[102:105], v146 offset:35840
	ds_read_b128 v[234:237], v146 offset:36864
	ds_read_b128 v[238:241], v146 offset:37888
	ds_read_b128 v[242:245], v146 offset:38912
	ds_read_b128 v[246:249], v146 offset:39936
	global_load_lds_dwordx4 v[2:3], off nt
	v_lshl_add_u64 v[2:3], s[22:23], 0, v[132:133]
	s_mov_b32 m0, s37
	s_nop 0
	global_load_lds_dwordx4 v[2:3], off nt
	s_waitcnt vmcnt(8)
	s_waitcnt lgkmcnt(0)
	s_barrier
	s_setprio 1
	s_waitcnt lgkmcnt(0)
	v_mfma_f32_16x16x32_bf16 v[2:5], v[122:125], v[26:29], v[66:69]
	v_mfma_f32_16x16x32_bf16 v[34:37], v[126:129], v[30:33], v[2:5]
	v_mfma_f32_16x16x32_bf16 v[2:5], v[178:181], v[26:29], v[70:73]
	v_mfma_f32_16x16x32_bf16 v[38:41], v[206:209], v[30:33], v[2:5]
	v_mfma_f32_16x16x32_bf16 v[2:5], v[122:125], v[62:65], v[74:77]
	v_mfma_f32_16x16x32_bf16 v[18:21], v[126:129], v[102:105], v[2:5]
	v_mfma_f32_16x16x32_bf16 v[2:5], v[178:181], v[62:65], v[78:81]
	v_mfma_f32_16x16x32_bf16 v[22:25], v[206:209], v[102:105], v[2:5]
	v_mfma_f32_16x16x32_bf16 v[2:5], v[122:125], v[234:237], v[82:85]
	v_mfma_f32_16x16x32_bf16 v[10:13], v[126:129], v[238:241], v[2:5]
	v_mfma_f32_16x16x32_bf16 v[2:5], v[178:181], v[234:237], v[86:89]
	v_mfma_f32_16x16x32_bf16 v[14:17], v[206:209], v[238:241], v[2:5]
	v_mfma_f32_16x16x32_bf16 v[2:5], v[122:125], v[242:245], v[90:93]
	v_mfma_f32_16x16x32_bf16 v[6:9], v[178:181], v[242:245], v[94:97]
	v_mfma_f32_16x16x32_bf16 v[2:5], v[126:129], v[246:249], v[2:5]
	v_mfma_f32_16x16x32_bf16 v[6:9], v[206:209], v[246:249], v[6:9]
	s_setprio 0
	s_setprio 1
	v_mfma_f32_16x16x32_bf16 v[58:61], v[210:213], v[26:29], v[98:101]
	v_mfma_f32_16x16x32_bf16 v[26:29], v[226:229], v[26:29], v[182:185]
	v_mfma_f32_16x16x32_bf16 v[78:81], v[230:233], v[30:33], v[26:29]
	v_mfma_f32_16x16x32_bf16 v[26:29], v[210:213], v[62:65], v[186:189]
	v_mfma_f32_16x16x32_bf16 v[74:77], v[222:225], v[30:33], v[58:61]
	v_mfma_f32_16x16x32_bf16 v[58:61], v[222:225], v[102:105], v[26:29]
	v_mfma_f32_16x16x32_bf16 v[26:29], v[226:229], v[62:65], v[42:45]
	v_mfma_f32_16x16x32_bf16 v[62:65], v[230:233], v[102:105], v[26:29]
	v_mfma_f32_16x16x32_bf16 v[26:29], v[210:213], v[234:237], v[46:49]
	v_mfma_f32_16x16x32_bf16 v[42:45], v[222:225], v[238:241], v[26:29]
	v_mfma_f32_16x16x32_bf16 v[26:29], v[226:229], v[234:237], v[50:53]
	v_mfma_f32_16x16x32_bf16 v[46:49], v[230:233], v[238:241], v[26:29]
	v_mfma_f32_16x16x32_bf16 v[26:29], v[210:213], v[242:245], v[54:57]
	v_mfma_f32_16x16x32_bf16 v[30:33], v[226:229], v[242:245], v[190:193]
	v_mfma_f32_16x16x32_bf16 v[26:29], v[222:225], v[246:249], v[26:29]
	v_mfma_f32_16x16x32_bf16 v[30:33], v[230:233], v[246:249], v[30:33]
	s_setprio 0
	s_barrier
	s_mov_b32 m0, s90
	v_lshl_add_u64 v[50:51], v[250:251], 0, s[8:9]
	s_add_u32 s22, s42, 0x10080
	ds_read_b128 v[90:93], v146 offset:49152
	ds_read_b128 v[94:97], v146 offset:50176
	ds_read_b128 v[182:185], v146 offset:51200
	ds_read_b128 v[186:189], v146 offset:52224
	ds_read_b128 v[190:193], v146 offset:53248
	ds_read_b128 v[234:237], v146 offset:54272
	ds_read_b128 v[238:241], v146 offset:55296
	ds_read_b128 v[242:245], v146 offset:56320
	global_load_lds_dwordx4 v[50:51], off
	v_lshl_add_u64 v[50:51], v[252:253], 0, s[8:9]
	s_mov_b32 m0, s91
	s_addc_u32 s23, s43, 0
	global_load_lds_dwordx4 v[50:51], off
	v_lshl_add_u64 v[50:51], s[22:23], 0, v[134:135]
	s_mov_b32 m0, s92
	s_nop 0
	global_load_lds_dwordx4 v[50:51], off
	v_lshl_add_u64 v[50:51], s[22:23], 0, v[130:131]
	s_mov_b32 m0, s93
	s_nop 0
	global_load_lds_dwordx4 v[50:51], off
	v_lshl_add_u64 v[50:51], v[140:141], 0, s[8:9]
	s_mov_b32 m0, s44
	s_nop 0
	global_load_lds_dwordx4 v[50:51], off nt
	v_lshl_add_u64 v[50:51], v[142:143], 0, s[8:9]
	s_mov_b32 m0, s45
	s_nop 0
	global_load_lds_dwordx4 v[50:51], off nt
	s_waitcnt vmcnt(8)
	s_waitcnt lgkmcnt(0)
	s_barrier
	s_setprio 1
	s_waitcnt lgkmcnt(0)
	v_mfma_f32_16x16x32_bf16 v[50:53], v[122:125], v[90:93], v[150:153]
	v_mfma_f32_16x16x32_bf16 v[98:101], v[126:129], v[94:97], v[50:53]
	v_mfma_f32_16x16x32_bf16 v[50:53], v[178:181], v[90:93], v[154:157]
	v_mfma_f32_16x16x32_bf16 v[102:105], v[206:209], v[94:97], v[50:53]
	v_mfma_f32_16x16x32_bf16 v[50:53], v[122:125], v[182:185], v[158:161]
	v_mfma_f32_16x16x32_bf16 v[82:85], v[126:129], v[186:189], v[50:53]
	v_mfma_f32_16x16x32_bf16 v[50:53], v[178:181], v[182:185], v[162:165]
	v_mfma_f32_16x16x32_bf16 v[86:89], v[206:209], v[186:189], v[50:53]
	v_mfma_f32_16x16x32_bf16 v[50:53], v[122:125], v[190:193], v[166:169]
	v_mfma_f32_16x16x32_bf16 v[66:69], v[126:129], v[234:237], v[50:53]
	v_mfma_f32_16x16x32_bf16 v[50:53], v[178:181], v[190:193], v[170:173]
	v_mfma_f32_16x16x32_bf16 v[70:73], v[206:209], v[234:237], v[50:53]
	v_mfma_f32_16x16x32_bf16 v[50:53], v[122:125], v[238:241], v[106:109]
	v_mfma_f32_16x16x32_bf16 v[54:57], v[178:181], v[238:241], v[110:113]
	v_mfma_f32_16x16x32_bf16 v[50:53], v[126:129], v[242:245], v[50:53]
	v_mfma_f32_16x16x32_bf16 v[54:57], v[206:209], v[242:245], v[54:57]
	s_setprio 0
	s_setprio 1
	v_mfma_f32_16x16x32_bf16 v[106:109], v[210:213], v[90:93], v[114:117]
	v_mfma_f32_16x16x32_bf16 v[90:93], v[226:229], v[90:93], v[118:121]
	v_mfma_f32_16x16x32_bf16 v[126:129], v[230:233], v[94:97], v[90:93]
	v_mfma_f32_16x16x32_bf16 v[90:93], v[210:213], v[182:185], v[214:217]
	v_mfma_f32_16x16x32_bf16 v[114:117], v[222:225], v[186:189], v[90:93]
	v_mfma_f32_16x16x32_bf16 v[90:93], v[226:229], v[182:185], v[194:197]
	v_mfma_f32_16x16x32_bf16 v[118:121], v[230:233], v[186:189], v[90:93]
	v_mfma_f32_16x16x32_bf16 v[90:93], v[210:213], v[190:193], v[218:221]
	v_mfma_f32_16x16x32_bf16 v[122:125], v[222:225], v[94:97], v[106:109]
	v_mfma_f32_16x16x32_bf16 v[106:109], v[222:225], v[234:237], v[90:93]
	v_mfma_f32_16x16x32_bf16 v[90:93], v[226:229], v[190:193], v[198:201]
	v_mfma_f32_16x16x32_bf16 v[110:113], v[230:233], v[234:237], v[90:93]
	v_mfma_f32_16x16x32_bf16 v[90:93], v[210:213], v[238:241], v[202:205]
	v_mfma_f32_16x16x32_bf16 v[94:97], v[226:229], v[238:241], v[174:177]
	v_mfma_f32_16x16x32_bf16 v[90:93], v[222:225], v[242:245], v[90:93]
	v_mfma_f32_16x16x32_bf16 v[94:97], v[230:233], v[242:245], v[94:97]
	s_setprio 0
	s_barrier
	s_and_b64 vcc, exec, s[38:39]
	s_cbranch_vccnz .LBB0_543
	s_barrier

.LBB0_777:
	s_and_b64 vcc, exec, s[38:39]
	s_cbranch_vccnz .LBB0_811
	v_ashrrev_i32_e32 v2, 31, v16
	v_lshrrev_b32_e32 v2, 26, v2
	v_add_u32_e32 v2, v16, v2
	v_ashrrev_i32_e32 v10, 6, v2
	v_bfe_i32 v2, v16, 27, 1
	v_lshlrev_b32_e32 v1, 4, v16
	v_lshrrev_b32_e32 v2, 22, v2
	v_add_u32_e32 v2, v1, v2
	v_and_b32_e32 v2, 0xfffffc00, v2
	v_sub_u32_e32 v2, v1, v2
	v_lshrrev_b32_e32 v3, 4, v2
	v_bitop3_b32 v2, v3, v2, 32 bitop3:0x6c
	v_ashrrev_i32_e32 v4, 31, v2
	v_lshrrev_b32_e32 v4, 26, v4
	v_add_u32_e32 v4, v2, v4
	v_lshlrev_b32_e32 v3, 3, v10
	v_ashrrev_i32_e32 v11, 6, v4
	v_and_b32_e32 v4, 0xc0, v4
	v_and_b32_e32 v3, -16, v3
	v_sub_u32_e32 v2, v2, v4
	v_mov_b32_e32 v4, 1
	v_add_u32_e32 v3, v11, v3
	v_ashrrev_i16_sdwa v2, v4, sext(v2) dst_sel:DWORD dst_unused:UNUSED_PAD src0_sel:DWORD src1_sel:BYTE_0
	s_load_dwordx2 s[6:7], s[4:5], 0xe0
	v_lshlrev_b32_e32 v5, 5, v10
	v_bfe_i32 v12, v2, 0, 16
	v_lshlrev_b32_e32 v2, 1, v3
	v_lshrrev_b32_e32 v6, 2, v3
	v_and_b32_e32 v7, 3, v11
	s_mov_b32 s4, 0x3fffe0
	v_and_b32_e32 v5, 32, v5
	v_and_b32_e32 v2, 24, v2
	v_and_b32_e32 v6, 4, v6
	v_and_or_b32 v7, v3, s4, v7
	v_or3_b32 v2, v7, v6, v2
	v_add_lshl_u32 v5, v5, v12, 1
	v_add_u32_e32 v1, 0x2000, v1
	v_lshl_add_u32 v132, v2, 10, v5
	v_ashrrev_i32_e32 v2, 31, v1
	v_lshrrev_b32_e32 v2, 22, v2
	v_add_u32_e32 v2, v1, v2
	v_ashrrev_i32_e32 v13, 10, v2
	v_mul_i32_i24_e32 v2, 0x400, v13
	v_sub_u32_e32 v1, v1, v2
	v_lshrrev_b32_e32 v2, 4, v1
	v_bitop3_b32 v1, v2, v1, 32 bitop3:0x6c
	v_lshl_add_u32 v130, v3, 10, v5
	v_ashrrev_i32_e32 v3, 31, v1
	v_lshrrev_b32_e32 v3, 26, v3
	s_waitcnt lgkmcnt(0)
	s_add_u32 s24, s6, 0xa400000
	v_add_u32_e32 v3, v1, v3
	s_addc_u32 s25, s7, 0
	v_lshlrev_b32_e32 v2, 3, v13
	v_ashrrev_i32_e32 v14, 6, v3
	v_and_b32_e32 v3, 0xc0, v3
	s_add_u32 s26, s6, 0x2200000
	v_and_b32_e32 v2, -16, v2
	v_sub_u32_e32 v1, v1, v3
	s_addc_u32 s27, s7, 0
	v_add_u32_e32 v2, v14, v2
	v_ashrrev_i16_sdwa v1, v4, sext(v1) dst_sel:DWORD dst_unused:UNUSED_PAD src0_sel:DWORD src1_sel:BYTE_0
	v_and_b32_e32 v4, 3, v14
	s_ashr_i32 s9, s10, 6
	s_ashr_i32 s15, s14, 31
	s_ashr_i32 s17, s16, 31
	s_ashr_i32 s8, s10, 8
	v_and_or_b32 v4, v2, s4, v4
	s_lshl_b32 s37, s9, 10
	s_lshl_b64 s[4:5], s[16:17], 18
	s_lshl_b64 s[12:13], s[14:15], 18
	s_add_u32 s20, s26, s12
	v_lshlrev_b32_e32 v5, 5, v13
	v_bfe_i32 v15, v1, 0, 16
	v_lshlrev_b32_e32 v1, 1, v2
	v_lshrrev_b32_e32 v3, 2, v2
	s_addc_u32 s21, s27, s13
	s_add_i32 s44, s37, 0
	v_and_b32_e32 v5, 32, v5
	v_and_b32_e32 v1, 24, v1
	v_and_b32_e32 v3, 4, v3
	s_add_i32 m0, s44, 0x10000
	v_or3_b32 v1, v4, v3, v1
	v_add_lshl_u32 v3, v5, v15, 1
	global_load_lds_dwordx4 v132, s[20:21]
	s_add_i32 m0, s44, 0x12000
	v_lshl_add_u32 v136, v1, 10, v3
	s_add_u32 s12, s20, 0x20000
	global_load_lds_dwordx4 v136, s[20:21]
	s_addc_u32 s13, s21, 0
	s_add_i32 m0, s44, 0x14000
	s_mul_i32 s17, s14, 0x140000
	global_load_lds_dwordx4 v132, s[12:13]
	s_add_i32 m0, s44, 0x16000
	s_add_u32 s4, s24, s4
	s_addc_u32 s5, s25, s5
	s_mul_hi_i32 s11, s14, 0x140000
	s_add_u32 s18, s4, s17
	s_addc_u32 s19, s5, s11
	s_add_i32 s45, s44, 0x2000
	global_load_lds_dwordx4 v136, s[12:13]
	s_mov_b32 m0, s44
	s_add_u32 s4, s18, 0x20000
	v_lshl_add_u32 v134, v2, 10, v3
	global_load_lds_dwordx4 v130, s[18:19] nt
	s_mov_b32 m0, s45
	s_addc_u32 s5, s19, 0
	s_add_i32 s46, s44, 0x4000
	global_load_lds_dwordx4 v134, s[18:19] nt
	s_mov_b32 m0, s46
	s_add_i32 s47, s44, 0x6000
	global_load_lds_dwordx4 v130, s[4:5] nt
	s_mov_b32 m0, s47
	v_mov_b32_e32 v139, 0
	global_load_lds_dwordx4 v134, s[4:5] nt
	v_mov_b32_e32 v133, v139
	v_mov_b32_e32 v137, v139
	v_mov_b32_e32 v131, v139
	v_mov_b32_e32 v135, v139
	s_cmp_eq_u32 s8, 1
	s_movk_i32 s90, 0x400
	s_mov_b32 s91, 0
	v_lshl_add_u64 v[8:9], s[20:21], 0, v[132:133]
	v_lshl_add_u64 v[6:7], s[20:21], 0, v[136:137]
	v_lshl_add_u64 v[2:3], s[18:19], 0, v[130:131]
	s_cselect_b64 s[4:5], -1, 0
	s_cmp_lg_u32 s8, 1
	v_lshl_add_u64 v[4:5], s[18:19], 0, v[134:135]
	s_cbranch_scc1 .LBB0_780
	s_barrier
.LBB0_780:
	v_lshrrev_b32_e32 v18, 1, v16
	v_and_b32_e32 v19, 24, v18
	s_add_u32 s6, s6, 0xdc00000
	v_and_b32_e32 v17, 15, v16
	v_lshlrev_b32_e32 v20, 1, v19
	v_lshlrev_b32_e32 v16, 2, v16
	s_addc_u32 s7, s7, 0
	v_lshl_or_b32 v1, s8, 6, v17
	v_lshl_or_b32 v17, v17, 6, v20
	s_lshl_b32 s8, s8, 13
	v_and_b32_e32 v16, 32, v16
	v_bitop3_b32 v20, v17, s8, v16 bitop3:0xde
	s_lshl_b32 s8, s9, 5
	s_and_b32 s15, s8, 0x60
	s_lshl_b32 s8, s15, 7
	v_bitop3_b32 v141, v17, s8, v16 bitop3:0xde
	s_mov_b64 s[8:9], 0x80
	s_add_i32 m0, s44, 0x18000
	v_lshl_add_u64 v[8:9], v[8:9], 0, s[8:9]
	s_waitcnt vmcnt(2)
	s_barrier
	global_load_lds_dwordx4 v[8:9], off
	v_lshl_add_u64 v[6:7], v[6:7], 0, s[8:9]
	s_add_i32 m0, s44, 0x1a000
	s_add_i32 s92, s44, 0x8000
	s_add_i32 s93, s44, 0xa000
	global_load_lds_dwordx4 v[6:7], off
	v_lshl_add_u64 v[2:3], v[2:3], 0, s[8:9]
	s_mov_b32 m0, s92
	s_add_u32 s12, s20, 0x20080
	global_load_lds_dwordx4 v[2:3], off nt
	v_lshl_add_u64 v[2:3], v[4:5], 0, s[8:9]
	s_mov_b32 m0, s93
	s_addc_u32 s13, s21, 0
	global_load_lds_dwordx4 v[2:3], off nt
	s_add_i32 m0, s44, 0x1c000
	v_lshl_add_u64 v[2:3], s[12:13], 0, v[132:133]
	global_load_lds_dwordx4 v[2:3], off
	v_lshl_add_u64 v[2:3], s[12:13], 0, v[136:137]
	s_add_i32 m0, s44, 0x1e000
	s_cmpk_lt_u32 s10, 0x100
	global_load_lds_dwordx4 v[2:3], off
	v_or_b32_e32 v2, s15, v19
	v_lshrrev_b32_e32 v150, 4, v2
	v_lshlrev_b32_e32 v2, 13, v10
	v_and_b32_e32 v2, 0xffffc000, v2
	v_lshl_add_u32 v2, v11, 10, v2
	v_and_b32_e32 v3, 1, v10
	v_lshl_or_b32 v2, v3, 6, v2
	v_lshl_add_u32 v142, v12, 1, v2
	v_lshlrev_b32_e32 v2, 13, v13
	v_and_b32_e32 v2, 0xffffc000, v2
	s_waitcnt vmcnt(6)
	v_lshl_add_u32 v2, v14, 10, v2
	v_and_b32_e32 v3, 1, v13
	s_cselect_b64 s[10:11], -1, 0
	v_lshl_or_b32 v2, v3, 6, v2
	s_add_i32 s34, 0, 0x14000
	v_and_b32_e32 v140, 8, v18
	s_ashr_i32 s30, s36, 31
	s_ashr_i32 s31, s2, 31
	v_mov_b32_e32 v143, v139
	v_lshl_add_u32 v144, v15, 1, v2
	v_mov_b32_e32 v145, v139
	v_mov_b64_e32 v[146:147], 0x80
	v_mov_b64_e32 v[148:149], 0x7f
	v_add_u32_e32 v151, s3, v141
	v_add_u32_e32 v152, s34, v141
	v_add_u32_e32 v153, 0, v20
	s_barrier
	s_branch .LBB0_783

.LBB0_788:
	ds_read_b128 v[154:157], v151
	ds_read_b128 v[158:161], v151 offset:1024
	ds_read_b128 v[162:165], v151 offset:2048
	ds_read_b128 v[166:169], v151 offset:3072
	ds_read_b128 v[170:173], v152
	ds_read_b128 v[174:177], v152 offset:1024
	ds_read_b128 v[178:181], v152 offset:2048
	ds_read_b128 v[182:185], v152 offset:3072
	s_add_u32 s20, s18, 0xfffe0080
	s_addc_u32 s21, s19, -1
	s_cmp_eq_u32 s29, 4
	s_cselect_b32 s23, s95, s21
	s_cselect_b32 s22, s94, s20
	s_cselect_b32 s21, s13, s28
	s_cselect_b32 s20, s15, s17
	v_lshl_add_u64 v[218:219], s[18:19], 0, v[142:143]
	s_add_i32 m0, s44, 0xc000
	ds_read_b128 v[186:189], v153
	ds_read_b128 v[190:193], v153 offset:1024
	ds_read_b128 v[194:197], v153 offset:2048
	ds_read_b128 v[198:201], v153 offset:3072
	ds_read_b128 v[202:205], v153 offset:4096
	ds_read_b128 v[206:209], v153 offset:5120
	ds_read_b128 v[210:213], v153 offset:6144
	ds_read_b128 v[214:217], v153 offset:7168
	global_load_lds_dwordx4 v[218:219], off nt
	v_lshl_add_u64 v[218:219], s[18:19], 0, v[144:145]
	s_add_i32 m0, s44, 0xe000
	s_nop 0
	global_load_lds_dwordx4 v[218:219], off nt
	s_waitcnt vmcnt(8)
	s_waitcnt lgkmcnt(0)
	s_barrier
	s_setprio 1
	s_waitcnt lgkmcnt(0)
	v_mfma_f32_16x16x32_bf16 v[126:129], v[154:157], v[186:189], v[126:129]
	v_mfma_f32_16x16x32_bf16 v[122:125], v[162:165], v[186:189], v[122:125]
	v_mfma_f32_16x16x32_bf16 v[110:113], v[154:157], v[194:197], v[110:113]
	v_mfma_f32_16x16x32_bf16 v[106:109], v[162:165], v[194:197], v[106:109]
	v_mfma_f32_16x16x32_bf16 v[94:97], v[154:157], v[202:205], v[94:97]
	v_mfma_f32_16x16x32_bf16 v[90:93], v[162:165], v[202:205], v[90:93]
	v_mfma_f32_16x16x32_bf16 v[78:81], v[154:157], v[210:213], v[78:81]
	v_mfma_f32_16x16x32_bf16 v[74:77], v[162:165], v[210:213], v[74:77]
	v_mfma_f32_16x16x32_bf16 v[126:129], v[158:161], v[190:193], v[126:129]
	v_mfma_f32_16x16x32_bf16 v[122:125], v[166:169], v[190:193], v[122:125]
	v_mfma_f32_16x16x32_bf16 v[110:113], v[158:161], v[198:201], v[110:113]
	v_mfma_f32_16x16x32_bf16 v[106:109], v[166:169], v[198:201], v[106:109]
	v_mfma_f32_16x16x32_bf16 v[94:97], v[158:161], v[206:209], v[94:97]
	v_mfma_f32_16x16x32_bf16 v[90:93], v[166:169], v[206:209], v[90:93]
	v_mfma_f32_16x16x32_bf16 v[78:81], v[158:161], v[214:217], v[78:81]
	v_mfma_f32_16x16x32_bf16 v[74:77], v[166:169], v[214:217], v[74:77]
	s_setprio 0
	s_setprio 1
	v_mfma_f32_16x16x32_bf16 v[118:121], v[170:173], v[186:189], v[118:121]
	v_mfma_f32_16x16x32_bf16 v[114:117], v[178:181], v[186:189], v[114:117]
	v_mfma_f32_16x16x32_bf16 v[102:105], v[170:173], v[194:197], v[102:105]
	v_mfma_f32_16x16x32_bf16 v[98:101], v[178:181], v[194:197], v[98:101]
	v_mfma_f32_16x16x32_bf16 v[86:89], v[170:173], v[202:205], v[86:89]
	v_mfma_f32_16x16x32_bf16 v[82:85], v[178:181], v[202:205], v[82:85]
	v_mfma_f32_16x16x32_bf16 v[70:73], v[170:173], v[210:213], v[70:73]
	v_mfma_f32_16x16x32_bf16 v[66:69], v[178:181], v[210:213], v[66:69]
	v_mfma_f32_16x16x32_bf16 v[118:121], v[174:177], v[190:193], v[118:121]
	v_mfma_f32_16x16x32_bf16 v[114:117], v[182:185], v[190:193], v[114:117]
	v_mfma_f32_16x16x32_bf16 v[102:105], v[174:177], v[198:201], v[102:105]
	v_mfma_f32_16x16x32_bf16 v[98:101], v[182:185], v[198:201], v[98:101]
	v_mfma_f32_16x16x32_bf16 v[86:89], v[174:177], v[206:209], v[86:89]
	v_mfma_f32_16x16x32_bf16 v[82:85], v[182:185], v[206:209], v[82:85]
	v_mfma_f32_16x16x32_bf16 v[70:73], v[174:177], v[214:217], v[70:73]
	v_mfma_f32_16x16x32_bf16 v[66:69], v[182:185], v[214:217], v[66:69]
	s_setprio 0
	s_barrier
	s_add_i32 s35, s3, s37
	v_lshl_add_u64 v[218:219], s[20:21], 0, v[132:133]
	s_mov_b32 m0, s35
	ds_read_b128 v[186:189], v153 offset:16384
	ds_read_b128 v[190:193], v153 offset:17408
	ds_read_b128 v[194:197], v153 offset:18432
	ds_read_b128 v[198:201], v153 offset:19456
	ds_read_b128 v[202:205], v153 offset:20480
	ds_read_b128 v[206:209], v153 offset:21504
	ds_read_b128 v[210:213], v153 offset:22528
	ds_read_b128 v[214:217], v153 offset:23552
	global_load_lds_dwordx4 v[218:219], off
	s_add_i32 m0, s35, 0x2000
	s_add_u32 s40, s20, 0x20000
	v_lshl_add_u64 v[220:221], s[20:21], 0, v[136:137]
	s_addc_u32 s41, s21, 0
	s_add_i32 s35, s34, s37
	global_load_lds_dwordx4 v[220:221], off
	v_lshl_add_u64 v[222:223], s[40:41], 0, v[132:133]
	s_mov_b32 m0, s35
	v_lshl_add_u64 v[224:225], s[22:23], 0, v[134:135]
	global_load_lds_dwordx4 v[222:223], off
	v_lshl_add_u64 v[222:223], s[40:41], 0, v[136:137]
	s_add_i32 m0, s35, 0x2000
	s_nop 0
	global_load_lds_dwordx4 v[222:223], off
	v_lshl_add_u64 v[222:223], s[22:23], 0, v[130:131]
	s_mov_b32 m0, s44
	s_nop 0
	global_load_lds_dwordx4 v[222:223], off nt
	s_mov_b32 m0, s45
	s_nop 0
	global_load_lds_dwordx4 v[224:225], off nt
	s_waitcnt vmcnt(8)
	s_waitcnt lgkmcnt(0)
	s_barrier
	s_setprio 1
	s_waitcnt lgkmcnt(0)
	v_mfma_f32_16x16x32_bf16 v[62:65], v[154:157], v[186:189], v[62:65]
	v_mfma_f32_16x16x32_bf16 v[58:61], v[162:165], v[186:189], v[58:61]
	v_mfma_f32_16x16x32_bf16 v[46:49], v[154:157], v[194:197], v[46:49]
	v_mfma_f32_16x16x32_bf16 v[42:45], v[162:165], v[194:197], v[42:45]
	v_mfma_f32_16x16x32_bf16 v[30:33], v[154:157], v[202:205], v[30:33]
	v_mfma_f32_16x16x32_bf16 v[26:29], v[162:165], v[202:205], v[26:29]
	v_mfma_f32_16x16x32_bf16 v[14:17], v[154:157], v[210:213], v[14:17]
	v_mfma_f32_16x16x32_bf16 v[10:13], v[162:165], v[210:213], v[10:13]
	v_mfma_f32_16x16x32_bf16 v[62:65], v[158:161], v[190:193], v[62:65]
	v_mfma_f32_16x16x32_bf16 v[58:61], v[166:169], v[190:193], v[58:61]
	v_mfma_f32_16x16x32_bf16 v[46:49], v[158:161], v[198:201], v[46:49]
	v_mfma_f32_16x16x32_bf16 v[42:45], v[166:169], v[198:201], v[42:45]
	v_mfma_f32_16x16x32_bf16 v[30:33], v[158:161], v[206:209], v[30:33]
	v_mfma_f32_16x16x32_bf16 v[26:29], v[166:169], v[206:209], v[26:29]
	v_mfma_f32_16x16x32_bf16 v[14:17], v[158:161], v[214:217], v[14:17]
	v_mfma_f32_16x16x32_bf16 v[10:13], v[166:169], v[214:217], v[10:13]
	s_setprio 0
	s_setprio 1
	v_mfma_f32_16x16x32_bf16 v[54:57], v[170:173], v[186:189], v[54:57]
	v_mfma_f32_16x16x32_bf16 v[50:53], v[178:181], v[186:189], v[50:53]
	v_mfma_f32_16x16x32_bf16 v[38:41], v[170:173], v[194:197], v[38:41]
	v_mfma_f32_16x16x32_bf16 v[34:37], v[178:181], v[194:197], v[34:37]
	v_mfma_f32_16x16x32_bf16 v[22:25], v[170:173], v[202:205], v[22:25]
	v_mfma_f32_16x16x32_bf16 v[18:21], v[178:181], v[202:205], v[18:21]
	v_mfma_f32_16x16x32_bf16 v[6:9], v[170:173], v[210:213], v[6:9]
	v_mfma_f32_16x16x32_bf16 v[2:5], v[178:181], v[210:213], v[2:5]
	v_mfma_f32_16x16x32_bf16 v[54:57], v[174:177], v[190:193], v[54:57]
	v_mfma_f32_16x16x32_bf16 v[50:53], v[182:185], v[190:193], v[50:53]
	v_mfma_f32_16x16x32_bf16 v[38:41], v[174:177], v[198:201], v[38:41]
	v_mfma_f32_16x16x32_bf16 v[34:37], v[182:185], v[198:201], v[34:37]
	v_mfma_f32_16x16x32_bf16 v[22:25], v[174:177], v[206:209], v[22:25]
	v_mfma_f32_16x16x32_bf16 v[18:21], v[182:185], v[206:209], v[18:21]
	v_mfma_f32_16x16x32_bf16 v[6:9], v[174:177], v[214:217], v[6:9]
	v_mfma_f32_16x16x32_bf16 v[2:5], v[182:185], v[214:217], v[2:5]
	s_setprio 0
	s_barrier
	s_add_i32 s35, 0, 0x18000
	v_add_u32_e32 v138, s35, v141
	s_add_i32 s40, 0, 0x1c000
	ds_read_b128 v[154:157], v138
	ds_read_b128 v[158:161], v138 offset:1024
	ds_read_b128 v[162:165], v138 offset:2048
	ds_read_b128 v[166:169], v138 offset:3072
	v_add_u32_e32 v138, s40, v141
	ds_read_b128 v[170:173], v138
	ds_read_b128 v[174:177], v138 offset:1024
	ds_read_b128 v[178:181], v138 offset:2048
	ds_read_b128 v[182:185], v138 offset:3072
	s_add_u32 s22, s22, 0x20000
	s_addc_u32 s23, s23, 0
	s_mov_b32 m0, s46
	v_lshl_add_u64 v[226:227], s[22:23], 0, v[130:131]
	ds_read_b128 v[186:189], v153 offset:32768
	ds_read_b128 v[190:193], v153 offset:33792
	ds_read_b128 v[194:197], v153 offset:34816
	ds_read_b128 v[198:201], v153 offset:35840
	ds_read_b128 v[202:205], v153 offset:36864
	ds_read_b128 v[206:209], v153 offset:37888
	ds_read_b128 v[210:213], v153 offset:38912
	ds_read_b128 v[214:217], v153 offset:39936
	global_load_lds_dwordx4 v[226:227], off nt
	v_lshl_add_u64 v[226:227], s[22:23], 0, v[134:135]
	s_mov_b32 m0, s47
	s_nop 0
	global_load_lds_dwordx4 v[226:227], off nt
	s_waitcnt vmcnt(8)
	s_waitcnt lgkmcnt(0)
	s_barrier
	s_setprio 1
	s_waitcnt lgkmcnt(0)
	v_mfma_f32_16x16x32_bf16 v[126:129], v[154:157], v[186:189], v[126:129]
	v_mfma_f32_16x16x32_bf16 v[122:125], v[162:165], v[186:189], v[122:125]
	v_mfma_f32_16x16x32_bf16 v[110:113], v[154:157], v[194:197], v[110:113]
	v_mfma_f32_16x16x32_bf16 v[106:109], v[162:165], v[194:197], v[106:109]
	v_mfma_f32_16x16x32_bf16 v[94:97], v[154:157], v[202:205], v[94:97]
	v_mfma_f32_16x16x32_bf16 v[90:93], v[162:165], v[202:205], v[90:93]
	v_mfma_f32_16x16x32_bf16 v[78:81], v[154:157], v[210:213], v[78:81]
	v_mfma_f32_16x16x32_bf16 v[74:77], v[162:165], v[210:213], v[74:77]
	v_mfma_f32_16x16x32_bf16 v[126:129], v[158:161], v[190:193], v[126:129]
	v_mfma_f32_16x16x32_bf16 v[122:125], v[166:169], v[190:193], v[122:125]
	v_mfma_f32_16x16x32_bf16 v[110:113], v[158:161], v[198:201], v[110:113]
	v_mfma_f32_16x16x32_bf16 v[106:109], v[166:169], v[198:201], v[106:109]
	v_mfma_f32_16x16x32_bf16 v[94:97], v[158:161], v[206:209], v[94:97]
	v_mfma_f32_16x16x32_bf16 v[90:93], v[166:169], v[206:209], v[90:93]
	v_mfma_f32_16x16x32_bf16 v[78:81], v[158:161], v[214:217], v[78:81]
	v_mfma_f32_16x16x32_bf16 v[74:77], v[166:169], v[214:217], v[74:77]
	s_setprio 0
	s_setprio 1
	v_mfma_f32_16x16x32_bf16 v[118:121], v[170:173], v[186:189], v[118:121]
	v_mfma_f32_16x16x32_bf16 v[114:117], v[178:181], v[186:189], v[114:117]
	v_mfma_f32_16x16x32_bf16 v[102:105], v[170:173], v[194:197], v[102:105]
	v_mfma_f32_16x16x32_bf16 v[98:101], v[178:181], v[194:197], v[98:101]
	v_mfma_f32_16x16x32_bf16 v[86:89], v[170:173], v[202:205], v[86:89]
	v_mfma_f32_16x16x32_bf16 v[82:85], v[178:181], v[202:205], v[82:85]
	v_mfma_f32_16x16x32_bf16 v[70:73], v[170:173], v[210:213], v[70:73]
	v_mfma_f32_16x16x32_bf16 v[66:69], v[178:181], v[210:213], v[66:69]
	v_mfma_f32_16x16x32_bf16 v[118:121], v[174:177], v[190:193], v[118:121]
	v_mfma_f32_16x16x32_bf16 v[114:117], v[182:185], v[190:193], v[114:117]
	v_mfma_f32_16x16x32_bf16 v[102:105], v[174:177], v[198:201], v[102:105]
	v_mfma_f32_16x16x32_bf16 v[98:101], v[182:185], v[198:201], v[98:101]
	v_mfma_f32_16x16x32_bf16 v[86:89], v[174:177], v[206:209], v[86:89]
	v_mfma_f32_16x16x32_bf16 v[82:85], v[182:185], v[206:209], v[82:85]
	v_mfma_f32_16x16x32_bf16 v[70:73], v[174:177], v[214:217], v[70:73]
	v_mfma_f32_16x16x32_bf16 v[66:69], v[182:185], v[214:217], v[66:69]
	s_setprio 0
	s_barrier
	s_add_i32 s22, s35, s37
	v_lshl_add_u64 v[218:219], v[218:219], 0, s[8:9]
	s_mov_b32 m0, s22
	ds_read_b128 v[186:189], v153 offset:49152
	ds_read_b128 v[190:193], v153 offset:50176
	ds_read_b128 v[194:197], v153 offset:51200
	ds_read_b128 v[198:201], v153 offset:52224
	ds_read_b128 v[202:205], v153 offset:53248
	ds_read_b128 v[206:209], v153 offset:54272
	ds_read_b128 v[210:213], v153 offset:55296
	ds_read_b128 v[214:217], v153 offset:56320
	global_load_lds_dwordx4 v[218:219], off
	s_add_i32 m0, s22, 0x2000
	s_add_u32 s20, s20, 0x20080
	v_lshl_add_u64 v[218:219], v[220:221], 0, s[8:9]
	s_addc_u32 s21, s21, 0
	s_add_i32 s22, s40, s37
	global_load_lds_dwordx4 v[218:219], off
	v_lshl_add_u64 v[218:219], s[20:21], 0, v[132:133]
	s_mov_b32 m0, s22
	s_nop 0
	global_load_lds_dwordx4 v[218:219], off
	v_lshl_add_u64 v[218:219], s[20:21], 0, v[136:137]
	s_add_i32 m0, s22, 0x2000
	s_nop 0
	global_load_lds_dwordx4 v[218:219], off
	v_lshl_add_u64 v[218:219], v[222:223], 0, s[8:9]
	s_mov_b32 m0, s92
	s_nop 0
	global_load_lds_dwordx4 v[218:219], off nt
	v_lshl_add_u64 v[218:219], v[224:225], 0, s[8:9]
	s_mov_b32 m0, s93
	s_nop 0
	global_load_lds_dwordx4 v[218:219], off nt
	s_waitcnt vmcnt(8)
	s_waitcnt lgkmcnt(0)
	s_barrier
	s_setprio 1
	s_waitcnt lgkmcnt(0)
	v_mfma_f32_16x16x32_bf16 v[62:65], v[154:157], v[186:189], v[62:65]
	v_mfma_f32_16x16x32_bf16 v[58:61], v[162:165], v[186:189], v[58:61]
	v_mfma_f32_16x16x32_bf16 v[46:49], v[154:157], v[194:197], v[46:49]
	v_mfma_f32_16x16x32_bf16 v[42:45], v[162:165], v[194:197], v[42:45]
	v_mfma_f32_16x16x32_bf16 v[30:33], v[154:157], v[202:205], v[30:33]
	v_mfma_f32_16x16x32_bf16 v[26:29], v[162:165], v[202:205], v[26:29]
	v_mfma_f32_16x16x32_bf16 v[14:17], v[154:157], v[210:213], v[14:17]
	v_mfma_f32_16x16x32_bf16 v[10:13], v[162:165], v[210:213], v[10:13]
	v_mfma_f32_16x16x32_bf16 v[62:65], v[158:161], v[190:193], v[62:65]
	v_mfma_f32_16x16x32_bf16 v[58:61], v[166:169], v[190:193], v[58:61]
	v_mfma_f32_16x16x32_bf16 v[46:49], v[158:161], v[198:201], v[46:49]
	v_mfma_f32_16x16x32_bf16 v[42:45], v[166:169], v[198:201], v[42:45]
	v_mfma_f32_16x16x32_bf16 v[30:33], v[158:161], v[206:209], v[30:33]
	v_mfma_f32_16x16x32_bf16 v[26:29], v[166:169], v[206:209], v[26:29]
	v_mfma_f32_16x16x32_bf16 v[14:17], v[158:161], v[214:217], v[14:17]
	v_mfma_f32_16x16x32_bf16 v[10:13], v[166:169], v[214:217], v[10:13]
	s_setprio 0
	s_setprio 1
	v_mfma_f32_16x16x32_bf16 v[54:57], v[170:173], v[186:189], v[54:57]
	v_mfma_f32_16x16x32_bf16 v[50:53], v[178:181], v[186:189], v[50:53]
	v_mfma_f32_16x16x32_bf16 v[38:41], v[170:173], v[194:197], v[38:41]
	v_mfma_f32_16x16x32_bf16 v[34:37], v[178:181], v[194:197], v[34:37]
	v_mfma_f32_16x16x32_bf16 v[22:25], v[170:173], v[202:205], v[22:25]
	v_mfma_f32_16x16x32_bf16 v[18:21], v[178:181], v[202:205], v[18:21]
	v_mfma_f32_16x16x32_bf16 v[6:9], v[170:173], v[210:213], v[6:9]
	v_mfma_f32_16x16x32_bf16 v[2:5], v[178:181], v[210:213], v[2:5]
	v_mfma_f32_16x16x32_bf16 v[54:57], v[174:177], v[190:193], v[54:57]
	v_mfma_f32_16x16x32_bf16 v[50:53], v[182:185], v[190:193], v[50:53]
	v_mfma_f32_16x16x32_bf16 v[38:41], v[174:177], v[198:201], v[38:41]
	v_mfma_f32_16x16x32_bf16 v[34:37], v[182:185], v[198:201], v[34:37]
	v_mfma_f32_16x16x32_bf16 v[22:25], v[174:177], v[206:209], v[22:25]
	v_mfma_f32_16x16x32_bf16 v[18:21], v[182:185], v[206:209], v[18:21]
	v_mfma_f32_16x16x32_bf16 v[6:9], v[174:177], v[214:217], v[6:9]
	v_mfma_f32_16x16x32_bf16 v[2:5], v[182:185], v[214:217], v[2:5]
	s_setprio 0
	s_barrier
	s_add_i32 s29, s29, 2
	s_add_u32 s18, s18, 0x100
	s_addc_u32 s19, s19, 0
	s_add_u32 s17, s17, 0x100
	s_addc_u32 s28, s28, 0
	s_cmp_gt_u32 s29, 5
	s_cbranch_scc0 .LBB0_788
	s_and_b64 vcc, exec, s[10:11]
	s_cbranch_vccz .LBB0_791
	s_barrier
